# attention: cross-half max exchange via v_permlane32_swap, redundant MFMA hazard pads removed
# speedup vs baseline: 1.0154x; 1.0013x over previous
; DI void attn_phase(LAS unsigned char* lds, ArgsRef a, int l, int vcu, int G) {
;     ...
;                 mx = fmaxf(mx, __shfl_xor(mx, 32));
;                 const float mnew = fmaxf(mrun, mx), alpha = __builtin_amdgcn_exp2f(mrun - mnew);
;                 mrun = mnew;
;                 if (__builtin_amdgcn_ballot_w64(alpha != 1.0f) != 0ull) {
; #pragma unroll
;                     for (int i = 0; i < 16; ++i) { o0[i] *= alpha; o1[i] *= alpha; }
;                 }
.LBB0_388:
	v_mov_b32_e32 v64, v89
	v_mov_b32_e32 v65, v89
	s_nop 1
	v_permlane32_swap_b32_e32 v64, v65
	s_waitcnt lgkmcnt(0)
	v_max3_f32 v250, v88, v64, v65
	v_sub_f32_e32 v64, v88, v250
	v_exp_f32_e32 v204, v64
	s_nop 0
	v_cmp_neq_f32_e32 vcc, 1.0, v204
	s_cbranch_vccz .LBB0_390
	v_pk_mul_f32 v[46:47], v[46:47], v[204:205] op_sel_hi:[1,0]
	v_pk_mul_f32 v[44:45], v[44:45], v[204:205] op_sel_hi:[1,0]
	v_pk_mul_f32 v[42:43], v[42:43], v[204:205] op_sel_hi:[1,0]
	v_pk_mul_f32 v[40:41], v[40:41], v[204:205] op_sel_hi:[1,0]
	v_pk_mul_f32 v[38:39], v[38:39], v[204:205] op_sel_hi:[1,0]
	v_pk_mul_f32 v[36:37], v[36:37], v[204:205] op_sel_hi:[1,0]
	v_pk_mul_f32 v[34:35], v[34:35], v[204:205] op_sel_hi:[1,0]
	v_pk_mul_f32 v[32:33], v[32:33], v[204:205] op_sel_hi:[1,0]
	v_pk_mul_f32 v[62:63], v[62:63], v[204:205] op_sel_hi:[1,0]
	v_pk_mul_f32 v[60:61], v[60:61], v[204:205] op_sel_hi:[1,0]
	v_pk_mul_f32 v[58:59], v[58:59], v[204:205] op_sel_hi:[1,0]
	v_pk_mul_f32 v[56:57], v[56:57], v[204:205] op_sel_hi:[1,0]
	v_pk_mul_f32 v[54:55], v[54:55], v[204:205] op_sel_hi:[1,0]
	v_pk_mul_f32 v[52:53], v[52:53], v[204:205] op_sel_hi:[1,0]
	v_pk_mul_f32 v[50:51], v[50:51], v[204:205] op_sel_hi:[1,0]
	v_pk_mul_f32 v[48:49], v[48:49], v[204:205] op_sel_hi:[1,0]

; DI void attn_phase(LAS unsigned char* lds, ArgsRef a, int l, int vcu, int G) {
;     ...
;                 mx = fmaxf(mx, __shfl_xor(mx, 32));
;                 const float mnew = fmaxf(mrun, mx), alpha = __builtin_amdgcn_exp2f(mrun - mnew);
;                 mrun = mnew;
;                 if (__builtin_amdgcn_ballot_w64(alpha != 1.0f) != 0ull) {
; #pragma unroll
;                     for (int i = 0; i < 16; ++i) { o0[i] *= alpha; o1[i] *= alpha; }
;                 }
.LBB0_432:
	v_mov_b32_e32 v64, v88
	v_mov_b32_e32 v65, v88
	s_nop 1
	v_permlane32_swap_b32_e32 v64, v65
	s_waitcnt lgkmcnt(0)
	v_max3_f32 v153, v249, v64, v65
	v_sub_f32_e32 v64, v249, v153
	v_exp_f32_e32 v152, v64
	s_nop 0
	v_cmp_neq_f32_e32 vcc, 1.0, v152
	s_cbranch_vccz .LBB0_434
	v_pk_mul_f32 v[30:31], v[30:31], v[152:153] op_sel_hi:[1,0]
	v_pk_mul_f32 v[28:29], v[28:29], v[152:153] op_sel_hi:[1,0]
	v_pk_mul_f32 v[26:27], v[26:27], v[152:153] op_sel_hi:[1,0]
	v_pk_mul_f32 v[24:25], v[24:25], v[152:153] op_sel_hi:[1,0]
	v_pk_mul_f32 v[22:23], v[22:23], v[152:153] op_sel_hi:[1,0]
	v_pk_mul_f32 v[20:21], v[20:21], v[152:153] op_sel_hi:[1,0]
	v_pk_mul_f32 v[18:19], v[18:19], v[152:153] op_sel_hi:[1,0]
	v_pk_mul_f32 v[16:17], v[16:17], v[152:153] op_sel_hi:[1,0]
	v_pk_mul_f32 v[14:15], v[14:15], v[152:153] op_sel_hi:[1,0]
	v_pk_mul_f32 v[12:13], v[12:13], v[152:153] op_sel_hi:[1,0]
	v_pk_mul_f32 v[10:11], v[10:11], v[152:153] op_sel_hi:[1,0]
	v_pk_mul_f32 v[8:9], v[8:9], v[152:153] op_sel_hi:[1,0]
	v_pk_mul_f32 v[6:7], v[6:7], v[152:153] op_sel_hi:[1,0]
	v_pk_mul_f32 v[4:5], v[4:5], v[152:153] op_sel_hi:[1,0]
	v_pk_mul_f32 v[2:3], v[2:3], v[152:153] op_sel_hi:[1,0]
	v_pk_mul_f32 v[0:1], v[0:1], v[152:153] op_sel_hi:[1,0]

; DI unsigned pk2(float lo, float hi) { f32x2 v = {lo, hi}; return __builtin_bit_cast(unsigned, __builtin_convertvector(v, bf16x2v)); }
; #define MFMA32(a, b, c) __builtin_amdgcn_mfma_f32_32x32x16_bf16((a), (b), (c), 0, 0, 0)
; DI void attn_phase(LAS unsigned char* lds, ArgsRef a, int l, int vcu, int G) {
;     ...
;                 auto pv_chunk = [&](auto JC) { constexpr int J = decltype(JC)::value;
;                     float ps = 0.f;
; #pragma unroll
;                     for (int i = 0; i < 8; ++i) { const float p = __builtin_amdgcn_exp2f(s[8 * J + i] - mnew); s[8 * J + i] = p; ps += p; }
;                     u32x4 pw; pw.x = pk2(s[8 * J + 0], s[8 * J + 1]); pw.y = pk2(s[8 * J + 2], s[8 * J + 3]); pw.z = pk2(s[8 * J + 4], s[8 * J + 5]); pw.w = pk2(s[8 * J + 6], s[8 * J + 7]);
;                     const bf16x8 pf = __builtin_bit_cast(bf16x8, pw);
;                     o0 = MFMA32(vf[0][J], pf, o0);
;                     o1 = MFMA32(vf[1][J], pf, o1);
;                     return ps; };
;                 float ps;
;                 if (!loc || cb == HALF) { ps = pv_chunk(std::integral_constant<int, 0>{}); ps += pv_chunk(std::integral_constant<int, 1>{}); }
.LBB0_436:
	s_andn2_b64 vcc, exec, s[6:7]
	s_cbranch_vccnz .LBB0_438
	s_nop 0
	v_sub_f32_e32 v64, v144, v153
	v_exp_f32_e32 v210, v64
	v_sub_f32_e32 v64, v145, v153
	v_exp_f32_e32 v208, v64
	v_sub_f32_e32 v64, v146, v153
	v_exp_f32_e32 v206, v64
	v_sub_f32_e32 v64, v147, v153
	v_exp_f32_e32 v162, v64
	v_sub_f32_e32 v64, v148, v153
	v_exp_f32_e32 v160, v64
	v_sub_f32_e32 v64, v149, v153
	v_exp_f32_e32 v158, v64
	v_sub_f32_e32 v64, v150, v153
	v_exp_f32_e32 v156, v64
	v_sub_f32_e32 v64, v151, v153
	v_exp_f32_e32 v154, v64
	v_cvt_pk_bf16_f32 v64, v210, v208
	v_cvt_pk_bf16_f32 v65, v206, v162
	v_cvt_pk_bf16_f32 v66, v160, v158
	v_cvt_pk_bf16_f32 v67, v156, v154
	v_pk_add_f32 v[68:69], v[210:211], 0 op_sel_hi:[1,0]
	s_nop 0
	v_mfma_f32_32x32x16_bf16 v[16:31], v[136:139], v[64:67], v[16:31]
	v_add_f32_e64 v68, v208, v68
	v_add_f32_e64 v69, v209, v69
	v_add_f32_e64 v68, v206, v68
	v_add_f32_e64 v69, v207, v69
	v_add_f32_e64 v68, v162, v68
	v_add_f32_e64 v69, v163, v69
	v_pk_add_f32 v[68:69], v[160:161], v[68:69]
	v_mfma_f32_32x32x16_bf16 v[0:15], v[140:143], v[64:67], v[0:15]
	v_cvt_pk_bf16_f32 v64, v211, v209
	v_cvt_pk_bf16_f32 v65, v207, v163
	v_cvt_pk_bf16_f32 v66, v161, v159
	v_cvt_pk_bf16_f32 v67, v157, v155
	v_add_f32_e64 v68, v158, v68
	v_add_f32_e64 v69, v159, v69
	v_pk_add_f32 v[68:69], v[156:157], v[68:69]
	v_mfma_f32_32x32x16_bf16 v[16:31], v[128:131], v[64:67], v[16:31]
	v_add_f32_e64 v68, v154, v68
	v_add_f32_e64 v69, v155, v69
	v_add_f32_e32 v154, v68, v69
	v_mfma_f32_32x32x16_bf16 v[0:15], v[132:135], v[64:67], v[0:15]
